# neighbourhood-attention bias lookups: the 8 per-row rpb LDS reads of a score tile issued together before the per-element mask code instead of one read-wait per element
# speedup vs baseline: 1.0018x; 1.0018x over previous
.LBB0_242:
	v_add3_u32 v129, s90, v137, v158
	ds_read_b128 v[80:83], v129
	ds_read_b128 v[84:87], v129 offset:64
	ds_read_b128 v[88:91], v129 offset:4608
	ds_read_b128 v[92:95], v129 offset:4672
	ds_read_b128 v[96:99], v129 offset:9216
	ds_read_b128 v[100:103], v129 offset:9280
	ds_read_b128 v[104:107], v129 offset:13824
	ds_read_b128 v[108:111], v129 offset:13888
	v_add3_u32 v131, s90, v138, v115
	s_waitcnt lgkmcnt(7)
	v_mfma_f32_16x16x32_bf16 v[80:83], v[80:83], v[36:39], 0
	s_waitcnt lgkmcnt(5)
	v_mfma_f32_16x16x32_bf16 v[88:91], v[88:91], v[36:39], 0
	s_waitcnt lgkmcnt(3)
	v_mfma_f32_16x16x32_bf16 v[96:99], v[96:99], v[36:39], 0
	s_waitcnt lgkmcnt(1)
	v_mfma_f32_16x16x32_bf16 v[104:107], v[104:107], v[36:39], 0
	ds_read_b128 v[172:175], v129 offset:128
	ds_read_b128 v[226:229], v129 offset:4736
	ds_read_b128 v[230:233], v129 offset:9344
	ds_read_b128 v[234:237], v129 offset:13952
	v_mfma_f32_16x16x32_bf16 v[80:83], v[84:87], v[40:43], v[80:83]
	v_mfma_f32_16x16x32_bf16 v[84:87], v[92:95], v[40:43], v[88:91]
	v_mfma_f32_16x16x32_bf16 v[88:91], v[100:103], v[40:43], v[96:99]
	s_waitcnt lgkmcnt(4)
	v_mfma_f32_16x16x32_bf16 v[92:95], v[108:111], v[40:43], v[104:107]
	s_nop 0
	ds_read_b128 v[96:99], v129 offset:192
	ds_read_b128 v[100:103], v129 offset:4800
	ds_read_b128 v[238:241], v129 offset:9408
	ds_read_b128 v[242:245], v129 offset:14016
	s_waitcnt lgkmcnt(7)
	v_mfma_f32_16x16x32_bf16 v[104:107], v[172:175], v[32:35], v[80:83]
	s_waitcnt lgkmcnt(6)
	v_mfma_f32_16x16x32_bf16 v[172:175], v[226:229], v[32:35], v[84:87]
	s_waitcnt lgkmcnt(5)
	v_mfma_f32_16x16x32_bf16 v[226:229], v[230:233], v[32:35], v[88:91]
	s_waitcnt lgkmcnt(4)
	v_mfma_f32_16x16x32_bf16 v[230:233], v[234:237], v[32:35], v[92:95]
	ds_read_b64_tr_b16 v[84:85], v131 offset:18432
	ds_read_b64_tr_b16 v[80:81], v131 offset:18464
	ds_read_b64_tr_b16 v[88:89], v131 offset:18496
	ds_read_b64_tr_b16 v[92:93], v131 offset:18528
	ds_read_b64_tr_b16 v[86:87], v131 offset:23040
	ds_read_b64_tr_b16 v[82:83], v131 offset:23072
	ds_read_b64_tr_b16 v[90:91], v131 offset:23104
	ds_read_b64_tr_b16 v[94:95], v131 offset:23136
	s_waitcnt lgkmcnt(11)
	v_mfma_f32_16x16x32_bf16 v[108:111], v[96:99], v[28:31], v[104:107]
	s_waitcnt lgkmcnt(10)
	v_mfma_f32_16x16x32_bf16 v[104:107], v[100:103], v[28:31], v[172:175]
	s_waitcnt lgkmcnt(9)
	v_mfma_f32_16x16x32_bf16 v[100:103], v[238:241], v[28:31], v[226:229]
	s_waitcnt lgkmcnt(8)
	v_mfma_f32_16x16x32_bf16 v[96:99], v[242:245], v[28:31], v[230:233]
	s_lshl_b32 s62, s92, 1
	s_add_i32 s62, s62, s82
	s_cmp_ge_i32 s62, s78
	s_cselect_b64 s[14:15], -1, 0
	s_cmp_lt_i32 s62, s86
	s_cselect_b64 s[34:35], -1, 0
	v_sub_u32_e32 v129, s62, v146
	s_and_b64 s[60:61], s[14:15], s[34:35]
	v_med3_i32 v129, v129, -7, 7
	s_movk_i32 s14, 0x7c
	v_mul_lo_u32 v129, v129, s14
	v_add_u32_e32 v129, 0x12000, v129
	s_and_b64 vcc, s[40:41], s[54:55]
	s_cbranch_vccz .Lrpb1_skip
	v_lshl_add_u32 v226, v208, 2, v129
	v_lshl_add_u32 v227, v209, 2, v129
	v_lshl_add_u32 v228, v212, 2, v129
	v_lshl_add_u32 v229, v214, 2, v129
	v_lshl_add_u32 v230, v210, 2, v129
	v_lshl_add_u32 v231, v213, 2, v129
	v_lshl_add_u32 v232, v215, 2, v129
	v_lshl_add_u32 v233, v216, 2, v129
	ds_read_b32 v226, v226 offset:928
	ds_read_b32 v227, v227 offset:928
	ds_read_b32 v228, v228 offset:928
	ds_read_b32 v229, v229 offset:928
	ds_read_b32 v230, v230 offset:928
	ds_read_b32 v231, v231 offset:928
	ds_read_b32 v232, v232 offset:928
	ds_read_b32 v233, v233 offset:928
.Lrpb1_skip:
	s_and_b64 vcc, exec, s[12:13]
	v_mul_f32_e32 v108, 0x3e0293ee, v108
	s_cbranch_vccnz .LBB0_250
	s_mov_b64 s[14:15], -1
	s_and_b64 vcc, exec, s[40:41]
	s_cbranch_vccz .LBB0_247
	s_andn2_b64 vcc, exec, s[54:55]
	v_mov_b32_e32 v131, v108
	s_cbranch_vccnz .LBB0_246
	s_and_b64 s[14:15], s[60:61], s[50:51]
	s_and_b64 vcc, s[14:15], s[52:53]
	s_waitcnt lgkmcnt(0)
	v_fmamk_f32 v131, v226, 0x3fb8aa3b, v108
	v_cndmask_b32_e32 v131, v180, v131, vcc

.LBB0_250:
	v_cndmask_b32_e64 v131, 0, 1, s[40:41]
	v_mul_f32_e32 v109, 0x3e0293ee, v109
	s_and_b64 vcc, exec, s[12:13]
	v_cmp_ne_u32_e64 s[14:15], 1, v131
	s_cbranch_vccnz .LBB0_275
	s_and_b64 vcc, exec, s[14:15]
	s_mov_b64 s[34:35], -1
	s_cbranch_vccnz .LBB0_255
	s_andn2_b64 vcc, exec, s[54:55]
	v_mov_b32_e32 v131, v109
	s_cbranch_vccnz .LBB0_254
	v_readlane_b32 s34, v254, 28
	v_readlane_b32 s35, v254, 29
	v_readlane_b32 s92, v254, 30
	s_and_b64 s[34:35], s[60:61], s[34:35]
	v_readlane_b32 s93, v254, 31
	s_waitcnt lgkmcnt(0)
	v_fmamk_f32 v131, v227, 0x3fb8aa3b, v109
	s_and_b64 vcc, s[34:35], s[92:93]
	v_cndmask_b32_e32 v131, v180, v131, vcc

.LBB0_259:
	s_and_b64 vcc, exec, s[14:15]
	s_mov_b64 s[34:35], -1
	s_cbranch_vccnz .LBB0_263
	s_andn2_b64 vcc, exec, s[54:55]
	v_mov_b32_e32 v131, v111
	s_cbranch_vccnz .LBB0_262
	v_readlane_b32 s34, v254, 36
	v_readlane_b32 s35, v254, 37
	v_readlane_b32 s92, v254, 38
	s_and_b64 s[34:35], s[60:61], s[34:35]
	v_readlane_b32 s93, v254, 39
	s_waitcnt lgkmcnt(0)
	v_fmamk_f32 v131, v228, 0x3fb8aa3b, v111
	s_and_b64 vcc, s[34:35], s[92:93]
	v_cndmask_b32_e32 v131, v180, v131, vcc

.LBB0_267:
	s_and_b64 vcc, exec, s[14:15]
	s_mov_b64 s[34:35], -1
	s_cbranch_vccnz .LBB0_271
	s_andn2_b64 vcc, exec, s[54:55]
	v_mov_b32_e32 v131, v105
	s_cbranch_vccnz .LBB0_270
	v_readlane_b32 s34, v254, 44
	v_readlane_b32 s35, v254, 45
	v_readlane_b32 s92, v254, 46
	s_and_b64 s[34:35], s[60:61], s[34:35]
	v_readlane_b32 s93, v254, 47
	s_waitcnt lgkmcnt(0)
	v_fmamk_f32 v131, v229, 0x3fb8aa3b, v105
	s_and_b64 vcc, s[34:35], s[92:93]
	v_cndmask_b32_e32 v131, v180, v131, vcc

.LBB0_276:
	s_and_b64 vcc, exec, s[14:15]
	s_mov_b64 s[34:35], -1
	s_cbranch_vccnz .LBB0_280
	s_andn2_b64 vcc, exec, s[54:55]
	v_mov_b32_e32 v131, v110
	s_cbranch_vccnz .LBB0_279
	v_readlane_b32 s34, v254, 32
	v_readlane_b32 s35, v254, 33
	v_readlane_b32 s92, v254, 34
	s_and_b64 s[34:35], s[60:61], s[34:35]
	v_readlane_b32 s93, v254, 35
	s_waitcnt lgkmcnt(0)
	v_fmamk_f32 v131, v230, 0x3fb8aa3b, v110
	s_and_b64 vcc, s[34:35], s[92:93]
	v_cndmask_b32_e32 v131, v180, v131, vcc

.LBB0_284:
	s_and_b64 vcc, exec, s[14:15]
	s_mov_b64 s[34:35], -1
	s_cbranch_vccnz .LBB0_288
	s_andn2_b64 vcc, exec, s[54:55]
	v_mov_b32_e32 v131, v104
	s_cbranch_vccnz .LBB0_287
	v_readlane_b32 s34, v254, 40
	v_readlane_b32 s35, v254, 41
	v_readlane_b32 s92, v254, 42
	s_and_b64 s[34:35], s[60:61], s[34:35]
	v_readlane_b32 s93, v254, 43
	s_waitcnt lgkmcnt(0)
	v_fmamk_f32 v131, v231, 0x3fb8aa3b, v104
	s_and_b64 vcc, s[34:35], s[92:93]
	v_cndmask_b32_e32 v131, v180, v131, vcc

.LBB0_292:
	s_and_b64 vcc, exec, s[14:15]
	s_mov_b64 s[34:35], -1
	s_cbranch_vccnz .LBB0_296
	s_andn2_b64 vcc, exec, s[54:55]
	v_mov_b32_e32 v131, v106
	s_cbranch_vccnz .LBB0_295
	v_readlane_b32 s34, v254, 48
	v_readlane_b32 s35, v254, 49
	v_readlane_b32 s92, v254, 50
	s_and_b64 s[34:35], s[60:61], s[34:35]
	v_readlane_b32 s93, v254, 51
	s_waitcnt lgkmcnt(0)
	v_fmamk_f32 v131, v232, 0x3fb8aa3b, v106
	s_and_b64 vcc, s[34:35], s[92:93]
	v_cndmask_b32_e32 v131, v180, v131, vcc

.LBB0_299:
	s_and_b64 vcc, exec, s[14:15]
	s_mov_b64 s[34:35], -1
	s_cbranch_vccnz .LBB0_303
	s_andn2_b64 vcc, exec, s[54:55]
	v_mov_b32_e32 v131, v107
	s_cbranch_vccnz .LBB0_302
	v_readlane_b32 s34, v254, 52
	v_readlane_b32 s35, v254, 53
	s_and_b64 s[34:35], s[60:61], s[34:35]
	v_readlane_b32 s60, v254, 54
	v_readlane_b32 s61, v254, 55
	s_waitcnt lgkmcnt(0)
	v_fmamk_f32 v129, v233, 0x3fb8aa3b, v107
	s_and_b64 vcc, s[34:35], s[60:61]
	v_cndmask_b32_e32 v131, v180, v129, vcc

.LBB0_306:
	s_or_b32 s62, s62, 1
	s_cmp_ge_i32 s62, s78
	s_cselect_b64 s[34:35], -1, 0
	s_cmp_lt_i32 s62, s86
	s_cselect_b64 s[60:61], -1, 0
	v_sub_u32_e32 v129, s62, v146
	s_and_b64 s[60:61], s[34:35], s[60:61]
	v_med3_i32 v129, v129, -7, 7
	s_movk_i32 s34, 0x7c
	v_mul_lo_u32 v129, v129, s34
	v_add_u32_e32 v129, 0x12000, v129
	s_and_b64 vcc, s[40:41], s[54:55]
	s_cbranch_vccz .Lrpb2_skip
	v_lshl_add_u32 v234, v208, 2, v129
	v_lshl_add_u32 v235, v218, 2, v129
	v_lshl_add_u32 v236, v220, 2, v129
	v_lshl_add_u32 v237, v222, 2, v129
	v_lshl_add_u32 v238, v217, 2, v129
	v_lshl_add_u32 v239, v219, 2, v129
	v_lshl_add_u32 v240, v221, 2, v129
	v_lshl_add_u32 v241, v223, 2, v129
	ds_read_b32 v234, v234 offset:928
	ds_read_b32 v235, v235 offset:928
	ds_read_b32 v236, v236 offset:928
	ds_read_b32 v237, v237 offset:928
	ds_read_b32 v238, v238 offset:928
	ds_read_b32 v239, v239 offset:928
	ds_read_b32 v240, v240 offset:928
	ds_read_b32 v241, v241 offset:928
.Lrpb2_skip:
	s_and_b64 vcc, exec, s[12:13]
	v_mul_f32_e32 v100, 0x3e0293ee, v100
	s_cbranch_vccnz .LBB0_338
	s_and_b64 vcc, exec, s[14:15]
	s_mov_b64 s[34:35], -1
	s_cbranch_vccnz .LBB0_311
	s_andn2_b64 vcc, exec, s[54:55]
	v_mov_b32_e32 v131, v100
	s_cbranch_vccnz .LBB0_310
	s_and_b64 s[34:35], s[60:61], s[50:51]
	s_and_b64 vcc, s[34:35], s[52:53]
	s_waitcnt lgkmcnt(0)
	v_fmamk_f32 v131, v234, 0x3fb8aa3b, v100
	v_cndmask_b32_e32 v131, v180, v131, vcc

.LBB0_315:
	s_and_b64 vcc, exec, s[14:15]
	s_mov_b64 s[34:35], -1
	s_cbranch_vccnz .LBB0_319
	s_andn2_b64 vcc, exec, s[54:55]
	v_mov_b32_e32 v131, v102
	s_cbranch_vccnz .LBB0_318
	v_readlane_b32 s34, v254, 60
	v_readlane_b32 s35, v254, 61
	v_readlane_b32 s92, v254, 62
	s_and_b64 s[34:35], s[60:61], s[34:35]
	v_readlane_b32 s93, v254, 63
	s_waitcnt lgkmcnt(0)
	v_fmamk_f32 v131, v235, 0x3fb8aa3b, v102
	s_and_b64 vcc, s[34:35], s[92:93]
	v_cndmask_b32_e32 v131, v180, v131, vcc

.LBB0_323:
	s_and_b64 vcc, exec, s[14:15]
	s_mov_b64 s[34:35], -1
	s_cbranch_vccnz .LBB0_327
	s_andn2_b64 vcc, exec, s[54:55]
	v_mov_b32_e32 v131, v96
	s_cbranch_vccnz .LBB0_326
	s_and_b64 s[34:35], s[60:61], s[94:95]
	s_and_b64 vcc, s[34:35], s[96:97]
	s_waitcnt lgkmcnt(0)
	v_fmamk_f32 v131, v236, 0x3fb8aa3b, v96
	v_cndmask_b32_e32 v131, v180, v131, vcc

.LBB0_331:
	s_and_b64 vcc, exec, s[14:15]
	s_mov_b64 s[34:35], -1
	s_cbranch_vccnz .LBB0_335
	s_andn2_b64 vcc, exec, s[54:55]
	v_mov_b32_e32 v131, v98
	s_cbranch_vccnz .LBB0_334
	s_and_b64 s[34:35], s[60:61], s[4:5]
	s_and_b64 vcc, s[34:35], s[6:7]
	s_waitcnt lgkmcnt(0)
	v_fmamk_f32 v131, v237, 0x3fb8aa3b, v98
	v_cndmask_b32_e32 v131, v180, v131, vcc

.LBB0_339:
	s_and_b64 vcc, exec, s[14:15]
	s_mov_b64 s[34:35], -1
	s_cbranch_vccnz .LBB0_343
	s_andn2_b64 vcc, exec, s[54:55]
	v_mov_b32_e32 v131, v101
	s_cbranch_vccnz .LBB0_342
	v_readlane_b32 s34, v254, 56
	v_readlane_b32 s35, v254, 57
	v_readlane_b32 s92, v254, 58
	s_and_b64 s[34:35], s[60:61], s[34:35]
	v_readlane_b32 s93, v254, 59
	s_waitcnt lgkmcnt(0)
	v_fmamk_f32 v131, v238, 0x3fb8aa3b, v101
	s_and_b64 vcc, s[34:35], s[92:93]
	v_cndmask_b32_e32 v131, v180, v131, vcc

.LBB0_347:
	s_and_b64 vcc, exec, s[14:15]
	s_mov_b64 s[34:35], -1
	s_cbranch_vccnz .LBB0_351
	s_andn2_b64 vcc, exec, s[54:55]
	v_mov_b32_e32 v131, v103
	s_cbranch_vccnz .LBB0_350
	v_readlane_b32 s34, v255, 0
	v_readlane_b32 s35, v255, 1
	v_readlane_b32 s92, v255, 2
	s_and_b64 s[34:35], s[60:61], s[34:35]
	v_readlane_b32 s93, v255, 3
	s_waitcnt lgkmcnt(0)
	v_fmamk_f32 v131, v239, 0x3fb8aa3b, v103
	s_and_b64 vcc, s[34:35], s[92:93]
	v_cndmask_b32_e32 v131, v180, v131, vcc

.LBB0_355:
	s_and_b64 vcc, exec, s[14:15]
	s_mov_b64 s[34:35], -1
	s_cbranch_vccnz .LBB0_359
	s_andn2_b64 vcc, exec, s[54:55]
	v_mov_b32_e32 v131, v97
	s_cbranch_vccnz .LBB0_358
	s_and_b64 s[34:35], s[60:61], s[98:99]
	s_and_b64 vcc, s[34:35], s[0:1]
	s_waitcnt lgkmcnt(0)
	v_fmamk_f32 v131, v240, 0x3fb8aa3b, v97
	v_cndmask_b32_e32 v131, v180, v131, vcc

.LBB0_363:
	s_and_b64 vcc, exec, s[14:15]
	s_mov_b64 s[12:13], -1
	s_cbranch_vccnz .LBB0_367
	s_andn2_b64 vcc, exec, s[54:55]
	v_mov_b32_e32 v131, v99
	s_cbranch_vccnz .LBB0_366
	s_and_b64 s[12:13], s[60:61], s[8:9]
	s_and_b64 vcc, s[12:13], s[10:11]
	s_waitcnt lgkmcnt(0)
	v_fmamk_f32 v129, v241, 0x3fb8aa3b, v99
	v_cndmask_b32_e32 v131, v180, v129, vcc
